# stick-breaking loop: K/V prefetch loads no longer waited before the score MFMAs (query fragments drained once in the unit prologue)
# baseline (speedup 1.0000x reference)
; #define LAS __attribute__((address_space(3)))
; template <int MODE>
; DI void attn_unit(unsigned char* ws, int b, int h, int qb, LAS unsigned char* lds, bool do_store = true) {
;     ...
;     const int qcol = MODE == 0 ? h * 96 : h * 64, kcol = MODE == 0 ? h * 128 : 512 + h * 64, vcol = MODE == 0 ? h * 128 + 64 : 1024 + h * 64, ocol = h * 64;
;     const int tid = tid_opaque(), lane = tid & 63, w = __builtin_amdgcn_readfirstlane(tid >> 6), r = lane & 31, hh = lane >> 5;
;     const int q0 = qb * 256; const long rowbase = (long)b * SEQ;
;     const int qg = q0 + 32 * w + r;
;     bf16x8 qf[NS];
;     { const bf16_t* qrow = Qb + (size_t)(rowbase + qg) * QPITCH + qcol + 8 * hh;
; #pragma unroll
;       for (int s = 0; s < NS; ++s) qf[s] = *(const bf16x8*)(qrow + 16 * s); }
;     unsigned mysel = 0;
;     if (MODE == 2) {
;         if (tid < 256) {
;             const bf16_t* qr = Qb + (size_t)(rowbase + q0 + tid) * QPITCH + qcol;
;             float qv[64];
; #pragma unroll
;             for (int c8 = 0; c8 < 8; ++c8) { const u32x4 u = *(const u32x4*)(qr + c8 * 8);
; #pragma unroll
;                 for (int e = 0; e < 4; ++e) { qv[c8 * 8 + 2 * e] = bf_lo(u[e]); qv[c8 * 8 + 2 * e + 1] = bf_hi(u[e]); } }
;             const float* km = (const float*)(ws + WS_KMEAN) + (size_t)((b * 8 + h) * 16) * 64;
;             float v0 = -INFINITY, v1 = -INFINITY, v2 = -INFINITY; int i0 = -1, i1 = -1, i2 = -1;
;             for (int n = 0; n < qb; ++n) { float d = 0.f;
; #pragma unroll
;                 for (int e = 0; e < 64; ++e) d += qv[e] * km[n * 64 + e];
;                 if (d > v0) { v2 = v1; i2 = i1; v1 = v0; i1 = i0; v0 = d; i0 = n; }
;                 else if (d > v1) { v2 = v1; i2 = i1; v1 = d; i1 = n; }
;                 else if (d > v2) { v2 = d; i2 = n; } }
;             unsigned mk = 0; if (i0 >= 0) mk |= 1u << i0; if (i1 >= 0) mk |= 1u << i1; if (i2 >= 0) mk |= 1u << i2;
;             *(LAS unsigned*)(lds + AT_SEL + tid * 4) = mk;
;         }
;         __syncthreads();
;         mysel = *(LAS unsigned*)(lds + AT_SEL + (32 * w + r) * 4);
;     }
;     const int kkey = tid >> 3, kch = tid & 7, pkey = (tid & 255) >> 2, pch = tid & 3;
;     u32x4 kr[2], vr[2], pr[2];
;     pr[0] = (u32x4){0u, 0u, 0u, 0u}; pr[1] = pr[0];
;     ...
;     const int kt_hi = qb * 4 + 3;
;     AT_LOADG(kt_hi, 0); AT_LOADG(kt_hi - 1, 1); AT_STORE(0, 0);
;     __syncthreads();
.LBB0_101:
	s_or_b64 exec, exec, s[38:39]
	v_mov_b32_e32 v0, s93
	s_waitcnt lgkmcnt(0)
	s_barrier
	ds_read_b32 v0, v0
	s_movk_i32 s2, 0xbff
	s_mov_b64 s[38:39], -1
	s_waitcnt lgkmcnt(0)
	v_cmp_lt_i32_e32 vcc, s2, v0
	v_readfirstlane_b32 s14, v0
	s_cbranch_vccnz .LBB0_96
	s_cmpk_gt_i32 s14, 0x7ff
	s_cbranch_scc0 .LBB0_124
	s_add_i32 s2, s14, 0xfffff800
	s_lshr_b32 s2, s2, 6
	s_sub_i32 s44, 15, s2
	s_lshl_b32 s15, s14, 7
	s_and_b32 s38, s15, 0x380
	s_lshl_b32 s15, s44, 2
	v_mov_b32_e32 v12, v210
	s_lshl_b32 s2, s14, 9
	s_or_b32 s15, s15, 3
	s_and_b32 s2, s2, 0x7000
	v_ashrrev_i32_e32 v4, 3, v12
	s_lshl_b32 s30, s15, 6
	s_or_b32 s30, s30, s2
	s_mov_b32 s31, s3
	v_ashrrev_i32_e32 v5, 31, v4
	v_mov_b64_e32 v[2:3], s[18:19]
	v_lshl_add_u64 v[6:7], v[4:5], 0, s[30:31]
	v_mad_u64_u32 v[8:9], s[30:31], v6, s88, v[2:3]
	v_readfirstlane_b32 s30, v12
	s_ashr_i32 s31, s30, 6
	s_mov_b32 s39, s3
	v_mad_i32_i24 v9, v7, s88, v9
	v_lshlrev_b32_e32 v0, 4, v12
	s_lshl_b32 s30, s44, 8
	s_lshl_b32 s44, s31, 5
	v_lshl_add_u64 v[6:7], v[8:9], 0, s[38:39]
	v_and_b32_e32 v8, 0x70, v0
	v_mov_b32_e32 v9, v1
	v_and_b32_e32 v13, 31, v12
	s_or_b32 s45, s2, s30
	s_add_i32 s30, s44, s30
	v_lshl_add_u64 v[6:7], v[6:7], 0, v[8:9]
	s_waitcnt vmcnt(0)
	v_or_b32_e32 v130, s30, v13
	global_load_dwordx4 v[66:69], v[6:7], off offset:1024
	global_load_dwordx4 v[70:73], v[6:7], off offset:2048
	v_add_u32_e32 v6, s45, v4
	v_ashrrev_i32_e32 v131, 31, v130
	v_add_u32_e32 v6, 0x80, v6
	v_lshl_add_u64 v[10:11], v[130:131], 0, s[2:3]
	v_mad_i64_i32 v[6:7], s[44:45], v6, s88, v[2:3]
	v_mad_u64_u32 v[2:3], s[44:45], v10, s88, v[2:3]
	v_bfe_u32 v14, v12, 5, 1
	v_mad_i32_i24 v3, v11, s88, v3
	v_lshlrev_b32_e32 v0, 4, v14
	v_lshl_add_u64 v[6:7], v[6:7], 0, s[38:39]
	v_lshl_add_u64 v[132:133], v[2:3], 0, s[38:39]
	v_lshl_add_u64 v[6:7], v[6:7], 0, v[8:9]
	v_lshl_add_u64 v[2:3], v[132:133], 0, v[0:1]
	global_load_dwordx4 v[90:93], v[6:7], off offset:1024
	global_load_dwordx4 v[94:97], v[6:7], off offset:2048
	global_load_dwordx4 v[74:77], v[2:3], off
	global_load_dwordx4 v[78:81], v[2:3], off offset:32
	global_load_dwordx4 v[82:85], v[2:3], off offset:64
	global_load_dwordx4 v[86:89], v[2:3], off offset:96
	s_movk_i32 s39, 0x90
	v_and_b32_e32 v2, 63, v12
	v_mul_lo_u32 v10, v4, s39
	s_lshl_b32 s31, s31, 2
	s_or_b32 s52, s30, 31
	v_lshrrev_b32_e32 v3, 2, v12
	v_and_b32_e32 v6, 16, v12
	v_lshlrev_b32_e32 v7, 2, v12
	v_cmp_gt_u32_e64 s[44:45], 32, v2
	v_lshlrev_b32_e32 v131, 2, v14
	v_cmp_eq_u32_e64 s[46:47], 0, v2
	v_add_u32_e32 v2, 0, v10
	s_add_u32 s38, s18, s38
	v_and_or_b32 v6, v7, 12, v6
	v_mad_u32_u24 v140, v13, s39, 0
	v_and_or_b32 v7, v3, 3, v131
	v_lshl_add_u64 v[134:135], v[4:5], 0, s[2:3]
	v_add_u32_e32 v151, v2, v8
	v_mad_u64_u32 v[2:3], s[48:49], v4, 48, v[2:3]
	s_movk_i32 s2, 0xc0
	s_addc_u32 s39, s19, 0
	v_mov_b32_e32 v16, v1
	v_mov_b32_e32 v17, v1
	v_lshlrev_b32_e32 v141, 1, v6
	v_mad_u32_u24 v152, v7, s2, 0
	v_add_u32_e32 v153, v2, v8
	v_lshl_add_u64 v[136:137], s[38:39], 0, v[8:9]
	v_mov_b32_e32 v2, v1
	v_mov_b32_e32 v3, v1
	v_mov_b32_e32 v4, v1
	v_mov_b32_e32 v5, v1
	v_mov_b32_e32 v6, v1
	v_mov_b32_e32 v7, v1
	v_mov_b32_e32 v8, v1
	v_mov_b32_e32 v10, v1
	v_mov_b32_e32 v11, v1
	v_mov_b32_e32 v12, v1
	v_mov_b32_e32 v13, v1
	v_mov_b32_e32 v14, v1
	v_mov_b32_e32 v15, v1
	v_mov_b64_e32 v[32:33], v[16:17]
	v_or_b32_e32 v142, 32, v131
	v_or_b32_e32 v143, 1, v131
	v_or_b32_e32 v144, 33, v131
	v_or_b32_e32 v145, 2, v131
	v_or_b32_e32 v146, 34, v131
	v_or_b32_e32 v147, 3, v131
	v_or_b32_e32 v148, 35, v131
	v_or_b32_e32 v149, 8, v131
	v_or_b32_e32 v150, 40, v131
	v_or_b32_e32 v154, 9, v131
	v_or_b32_e32 v155, 41, v131
	v_or_b32_e32 v156, 10, v131
	v_or_b32_e32 v157, 42, v131
	v_or_b32_e32 v158, 11, v131
	v_or_b32_e32 v159, 43, v131
	v_or_b32_e32 v160, 16, v131
	v_or_b32_e32 v161, 48, v131
	v_or_b32_e32 v162, 17, v131
	v_or_b32_e32 v163, 49, v131
	v_or_b32_e32 v164, 18, v131
	v_or_b32_e32 v165, 50, v131
	v_or_b32_e32 v166, 19, v131
	v_or_b32_e32 v167, 51, v131
	v_or_b32_e32 v168, 24, v131
	v_or_b32_e32 v169, 56, v131
	v_or_b32_e32 v170, 25, v131
	v_or_b32_e32 v171, 57, v131
	v_or_b32_e32 v176, 26, v131
	v_or_b32_e32 v177, 58, v131
	v_or_b32_e32 v178, 27, v131
	v_or_b32_e32 v179, 59, v131
	v_mov_b32_e32 v138, 1.0
	s_mov_b64 s[48:49], 0
	v_mov_b64_e32 v[30:31], v[14:15]
	v_mov_b64_e32 v[28:29], v[12:13]
	v_mov_b64_e32 v[26:27], v[10:11]
	v_mov_b64_e32 v[24:25], v[8:9]
	v_mov_b64_e32 v[22:23], v[6:7]
	v_mov_b64_e32 v[20:21], v[4:5]
	v_mov_b64_e32 v[18:19], v[2:3]
	s_waitcnt vmcnt(7)
	ds_write_b128 v151, v[66:69]
	s_waitcnt vmcnt(6)
	ds_write_b128 v153, v[70:73] offset:32768
	s_waitcnt vmcnt(0)
	s_waitcnt lgkmcnt(0)
	s_barrier
	s_branch .LBB0_106

; #define LAS __attribute__((address_space(3)))
; template <int MODE>
; DI void attn_unit(unsigned char* ws, int b, int h, int qb, LAS unsigned char* lds, bool do_store = true) {
;     ...
;         if (kt >= 2) AT_LOADG(kt - 2, half);
;         if (kt * 64 <= qmax_w && !wfin) {
;             const LAS unsigned char* kb = lds + (half ? AT_K1 : AT_K0) + r * KP + hh * 16;
;             f32x16 p0, p1;
; #pragma unroll
;             for (int s = 0; s < NS; ++s) {
;                 const bf16x8 k0 = *(const LAS bf16x8*)(kb + s * 32), k1 = *(const LAS bf16x8*)(kb + 32 * KP + s * 32);
;                 if (s == 0) { p0 = MFMA32(k0, qf[s], zero16); p1 = MFMA32(k1, qf[s], zero16); }
;                 else { p0 = MFMA32(k0, qf[s], p0); p1 = MFMA32(k1, qf[s], p1); }
;             }
;             if (MODE != 1) {
;                 bf16x8 qe = qx;
;                 if (MODE == 2) { const int nbk = kt >> 2; const bool dead = (nbk < qb) && !((mysel >> nbk) & 1u); qe = dead ? qbig : qx; }
;                 p0 = MFMA32(kx, qe, p0); p1 = MFMA32(kx, qe, p1);
;             }
;             bf16x8 vaf[4][2];
;             { const LAS unsigned char* vb = lds + (half ? AT_V1 : AT_V0) + voff;
; #pragma unroll
;               for (int f = 0; f < 4; ++f) { const LAS unsigned char* vp = vb + (16 * f) * VP;
;                   { const s16x4 lo = tr_read(vp), hi = tr_read(vp + 8 * VP); vaf[f][0] = __builtin_shufflevector(lo, hi, 0, 1, 2, 3, 4, 5, 6, 7); }
;                   { const s16x4 lo = tr_read(vp + 64), hi = tr_read(vp + 8 * VP + 64); vaf[f][1] = __builtin_shufflevector(lo, hi, 0, 1, 2, 3, 4, 5, 6, 7); } } }
;     ...
;             const bool needmask = (kt * 64 + 63 >= qmin_w);
;             const int kbase = kt * 64;
;             if (MODE == 1) {
;                 f32x16 k0v, k1v;
; #pragma unroll
;                 for (int i = 0; i < 16; ++i) {
;                     { const float z = p0[i]; const float e = fast_exp2(-fabsf(z)), rc = __builtin_amdgcn_rcpf(1.f + e), t = e * rc; float bt = z >= 0.f ? rc : t, kp = z >= 0.f ? t : rc;
;                       if (needmask && !(kbase + crow(i, hh) < qg)) { bt = 0.f; kp = 1.f; } p0[i] = bt; k0v[i] = kp; }
;                     { const float z = p1[i]; const float e = fast_exp2(-fabsf(z)), rc = __builtin_amdgcn_rcpf(1.f + e), t = e * rc; float bt = z >= 0.f ? rc : t, kp = z >= 0.f ? t : rc;
.LBB0_108:
	s_cmp_gt_i32 s50, s52
	s_cselect_b64 s[54:55], -1, 0
	s_or_b64 s[54:55], s[54:55], s[48:49]
	s_and_b64 vcc, exec, s[54:55]
	s_cbranch_vccnz .LBB0_110
	v_add_u32_e32 v106, v140, v0
	ds_read_b128 v[34:37], v106 offset:4608
	ds_read_b128 v[38:41], v106
	ds_read_b128 v[98:101], v106 offset:32
	ds_read_b128 v[102:105], v106 offset:4640
	s_or_b32 s2, s50, 63
	s_cmp_lt_i32 s2, s30
	s_waitcnt lgkmcnt(2)
	v_mfma_f32_32x32x16_bf16 v[50:65], v[38:41], v[74:77], 0
	s_cselect_b64 s[48:49], -1, 0
	v_add_u32_e32 v124, v152, v141
	v_mfma_f32_32x32x16_bf16 v[34:49], v[34:37], v[74:77], 0
	s_waitcnt lgkmcnt(1)
	v_mfma_f32_32x32x16_bf16 v[50:65], v[98:101], v[78:81], v[50:65]
	s_waitcnt lgkmcnt(0)
	v_mfma_f32_32x32x16_bf16 v[34:49], v[102:105], v[78:81], v[34:49]
	ds_read_b128 v[98:101], v106 offset:4672
	ds_read_b128 v[102:105], v106 offset:64
	s_waitcnt lgkmcnt(0)
	v_mfma_f32_32x32x16_bf16 v[50:65], v[102:105], v[82:85], v[50:65]
	v_mfma_f32_32x32x16_bf16 v[34:49], v[98:101], v[82:85], v[34:49]
	ds_read_b128 v[98:101], v106 offset:4704
	ds_read_b128 v[102:105], v106 offset:96
	s_waitcnt lgkmcnt(0)
	v_mfma_f32_32x32x16_bf16 v[50:65], v[102:105], v[86:89], v[50:65]
	v_mfma_f32_32x32x16_bf16 v[34:49], v[98:101], v[86:89], v[34:49]
	s_nop 10
	v_exp_f32_e64 v139, -|v50|
	v_cmp_le_f32_e32 vcc, 0, v50
	ds_read_b64_tr_b16 v[102:103], v124 offset:32768
	ds_read_b64_tr_b16 v[104:105], v124 offset:34304
	ds_read_b64_tr_b16 v[98:99], v124 offset:32832
	ds_read_b64_tr_b16 v[100:101], v124 offset:34368
	ds_read_b64_tr_b16 v[110:111], v124 offset:35840
	ds_read_b64_tr_b16 v[112:113], v124 offset:37376
	ds_read_b64_tr_b16 v[106:107], v124 offset:35904
	ds_read_b64_tr_b16 v[108:109], v124 offset:37440
	ds_read_b64_tr_b16 v[118:119], v124 offset:38912
	ds_read_b64_tr_b16 v[120:121], v124 offset:40448
	ds_read_b64_tr_b16 v[114:115], v124 offset:38976
	ds_read_b64_tr_b16 v[116:117], v124 offset:40512
	ds_read_b64_tr_b16 v[126:127], v124 offset:41984
	ds_read_b64_tr_b16 v[128:129], v124 offset:43520
	ds_read_b64_tr_b16 v[122:123], v124 offset:42048
	ds_read_b64_tr_b16 v[124:125], v124 offset:43584
	v_add_f32_e32 v180, 1.0, v139
	v_rcp_f32_e32 v180, v180
	s_nop 0
	v_mul_f32_e32 v139, v139, v180
	v_cndmask_b32_e32 v50, v139, v180, vcc
	v_cndmask_b32_e32 v139, v180, v139, vcc
	v_or_b32_e32 v180, s50, v131
	v_cmp_lt_i32_e32 vcc, v180, v130
	s_or_b64 vcc, s[48:49], vcc
	s_nop 0
	v_cndmask_b32_e32 v180, 1.0, v139, vcc
	v_exp_f32_e64 v139, -|v34|
	v_cndmask_b32_e32 v50, 0, v50, vcc
	v_cmp_le_f32_e32 vcc, 0, v34
	v_add_f32_e32 v181, 1.0, v139
	v_rcp_f32_e32 v181, v181
	s_nop 0
	v_mul_f32_e32 v139, v139, v181
	v_cndmask_b32_e32 v34, v139, v181, vcc
	v_cndmask_b32_e32 v139, v181, v139, vcc
	v_or_b32_e32 v181, s50, v142
	v_cmp_lt_i32_e32 vcc, v181, v130
	s_or_b64 vcc, s[48:49], vcc
	s_nop 0
	v_cndmask_b32_e32 v181, 0, v34, vcc
	v_exp_f32_e64 v34, -|v51|
	v_cndmask_b32_e32 v182, 1.0, v139, vcc
	v_cmp_le_f32_e32 vcc, 0, v51
	v_add_f32_e32 v139, 1.0, v34
	v_rcp_f32_e32 v139, v139
	s_nop 0
	v_mul_f32_e32 v34, v34, v139
	v_cndmask_b32_e32 v51, v34, v139, vcc
	v_cndmask_b32_e32 v139, v139, v34, vcc
	v_or_b32_e32 v34, s50, v143
	v_cmp_lt_i32_e32 vcc, v34, v130
	s_or_b64 vcc, s[48:49], vcc
	s_nop 0
	v_cndmask_b32_e32 v34, 0, v51, vcc
	v_cndmask_b32_e32 v51, 1.0, v139, vcc
	v_exp_f32_e64 v139, -|v35|
	v_cmp_le_f32_e32 vcc, 0, v35
	v_add_f32_e32 v183, 1.0, v139
	v_rcp_f32_e32 v183, v183
	s_nop 0
	v_mul_f32_e32 v139, v139, v183
	v_cndmask_b32_e32 v35, v139, v183, vcc
	v_cndmask_b32_e32 v139, v183, v139, vcc
	v_or_b32_e32 v183, s50, v144
	v_cmp_lt_i32_e32 vcc, v183, v130
	s_or_b64 vcc, s[48:49], vcc
	s_nop 0
	v_cndmask_b32_e32 v183, 0, v35, vcc
	v_exp_f32_e64 v35, -|v52|
	v_cndmask_b32_e32 v184, 1.0, v139, vcc
	v_cmp_le_f32_e32 vcc, 0, v52
	v_add_f32_e32 v139, 1.0, v35
	v_rcp_f32_e32 v139, v139
	s_nop 0
	v_mul_f32_e32 v35, v35, v139
	v_cndmask_b32_e32 v52, v35, v139, vcc
	v_cndmask_b32_e32 v139, v139, v35, vcc
	v_or_b32_e32 v35, s50, v145
	v_cmp_lt_i32_e32 vcc, v35, v130
	s_or_b64 vcc, s[48:49], vcc
	s_nop 0
	v_cndmask_b32_e32 v35, 0, v52, vcc
	v_cndmask_b32_e32 v52, 1.0, v139, vcc
	v_exp_f32_e64 v139, -|v36|
	v_cmp_le_f32_e32 vcc, 0, v36
	v_add_f32_e32 v185, 1.0, v139
	v_rcp_f32_e32 v185, v185
	s_nop 0
	v_mul_f32_e32 v139, v139, v185
	v_cndmask_b32_e32 v36, v139, v185, vcc
	v_cndmask_b32_e32 v139, v185, v139, vcc
	v_or_b32_e32 v185, s50, v146
	v_cmp_lt_i32_e32 vcc, v185, v130
	s_or_b64 vcc, s[48:49], vcc
	s_nop 0
	v_cndmask_b32_e32 v185, 0, v36, vcc
	v_exp_f32_e64 v36, -|v53|
	v_cndmask_b32_e32 v186, 1.0, v139, vcc
	v_cmp_le_f32_e32 vcc, 0, v53
	v_add_f32_e32 v139, 1.0, v36
	v_rcp_f32_e32 v139, v139
	s_nop 0
	v_mul_f32_e32 v36, v36, v139
	v_cndmask_b32_e32 v53, v36, v139, vcc
	v_cndmask_b32_e32 v139, v139, v36, vcc
	v_or_b32_e32 v36, s50, v147
	v_cmp_lt_i32_e32 vcc, v36, v130
	s_or_b64 vcc, s[48:49], vcc
	s_nop 0
	v_cndmask_b32_e32 v36, 0, v53, vcc
	v_cndmask_b32_e32 v53, 1.0, v139, vcc
	v_exp_f32_e64 v139, -|v37|
	v_cmp_le_f32_e32 vcc, 0, v37
	v_add_f32_e32 v187, 1.0, v139
	v_rcp_f32_e32 v187, v187
	s_nop 0
	v_mul_f32_e32 v139, v139, v187
	v_cndmask_b32_e32 v37, v139, v187, vcc
	v_cndmask_b32_e32 v139, v187, v139, vcc
	v_or_b32_e32 v187, s50, v148
	v_cmp_lt_i32_e32 vcc, v187, v130
	s_or_b64 vcc, s[48:49], vcc
	s_nop 0
	v_cndmask_b32_e32 v187, 0, v37, vcc
	v_exp_f32_e64 v37, -|v54|
	v_cndmask_b32_e32 v188, 1.0, v139, vcc
	v_cmp_le_f32_e32 vcc, 0, v54
	v_add_f32_e32 v139, 1.0, v37
	v_rcp_f32_e32 v139, v139
	s_nop 0
	v_mul_f32_e32 v37, v37, v139
	v_cndmask_b32_e32 v54, v37, v139, vcc
	v_cndmask_b32_e32 v139, v139, v37, vcc
	v_or_b32_e32 v37, s50, v149
	v_cmp_lt_i32_e32 vcc, v37, v130
; DI float fast_exp2(float x) { return __builtin_amdgcn_exp2f(x); }
; DI int crow(int i, int h) { return (i & 3) + 8 * (i >> 2) + 4 * h; }
; template <int MODE>
; DI void attn_unit(unsigned char* ws, int b, int h, int qb, LAS unsigned char* lds, bool do_store = true) {
;     ...
;                 for (int i = 0; i < 16; ++i) {
;                     { const float z = p0[i]; const float e = fast_exp2(-fabsf(z)), rc = __builtin_amdgcn_rcpf(1.f + e), t = e * rc; float bt = z >= 0.f ? rc : t, kp = z >= 0.f ? t : rc;
;                       if (needmask && !(kbase + crow(i, hh) < qg)) { bt = 0.f; kp = 1.f; } p0[i] = bt; k0v[i] = kp; }
;                     { const float z = p1[i]; const float e = fast_exp2(-fabsf(z)), rc = __builtin_amdgcn_rcpf(1.f + e), t = e * rc; float bt = z >= 0.f ? rc : t, kp = z >= 0.f ? t : rc;
;                       if (needmask && !(kbase + 32 + crow(i, hh) < qg)) { bt = 0.f; kp = 1.f; } p1[i] = bt; k1v[i] = kp; }
;                 }
	s_or_b64 vcc, s[48:49], vcc
	s_nop 0
	v_cndmask_b32_e32 v37, 0, v54, vcc
	v_cndmask_b32_e32 v54, 1.0, v139, vcc
	v_exp_f32_e64 v139, -|v38|
	v_cmp_le_f32_e32 vcc, 0, v38
	v_add_f32_e32 v189, 1.0, v139
	v_rcp_f32_e32 v189, v189
	s_nop 0
	v_mul_f32_e32 v139, v139, v189
	v_cndmask_b32_e32 v38, v139, v189, vcc
	v_cndmask_b32_e32 v139, v189, v139, vcc
	v_or_b32_e32 v189, s50, v150
	v_cmp_lt_i32_e32 vcc, v189, v130
	s_or_b64 vcc, s[48:49], vcc
	s_nop 0
	v_cndmask_b32_e32 v189, 0, v38, vcc
	v_exp_f32_e64 v38, -|v55|
	v_cndmask_b32_e32 v190, 1.0, v139, vcc
	v_cmp_le_f32_e32 vcc, 0, v55
	v_add_f32_e32 v139, 1.0, v38
	v_rcp_f32_e32 v139, v139
	s_nop 0
	v_mul_f32_e32 v38, v38, v139
	v_cndmask_b32_e32 v55, v38, v139, vcc
	v_cndmask_b32_e32 v139, v139, v38, vcc
	v_or_b32_e32 v38, s50, v154
	v_cmp_lt_i32_e32 vcc, v38, v130
	s_or_b64 vcc, s[48:49], vcc
	s_nop 0
	v_cndmask_b32_e32 v38, 0, v55, vcc
	v_cndmask_b32_e32 v55, 1.0, v139, vcc
	v_exp_f32_e64 v139, -|v39|
	v_cmp_le_f32_e32 vcc, 0, v39
	v_add_f32_e32 v191, 1.0, v139
	v_rcp_f32_e32 v191, v191
	s_nop 0
	v_mul_f32_e32 v139, v139, v191
	v_cndmask_b32_e32 v39, v139, v191, vcc
	v_cndmask_b32_e32 v139, v191, v139, vcc
	v_or_b32_e32 v191, s50, v155
	v_cmp_lt_i32_e32 vcc, v191, v130
	s_or_b64 vcc, s[48:49], vcc
	s_nop 0
	v_cndmask_b32_e32 v191, 0, v39, vcc
	v_exp_f32_e64 v39, -|v56|
	v_cndmask_b32_e32 v192, 1.0, v139, vcc
	v_cmp_le_f32_e32 vcc, 0, v56
	v_add_f32_e32 v139, 1.0, v39
	v_rcp_f32_e32 v139, v139
	s_nop 0
	v_mul_f32_e32 v39, v39, v139
	v_cndmask_b32_e32 v56, v39, v139, vcc
	v_cndmask_b32_e32 v139, v139, v39, vcc
	v_or_b32_e32 v39, s50, v156
	v_cmp_lt_i32_e32 vcc, v39, v130
	s_or_b64 vcc, s[48:49], vcc
	s_nop 0
	v_cndmask_b32_e32 v39, 0, v56, vcc
	v_cndmask_b32_e32 v56, 1.0, v139, vcc
	v_exp_f32_e64 v139, -|v40|
	v_cmp_le_f32_e32 vcc, 0, v40
	v_add_f32_e32 v193, 1.0, v139
	v_rcp_f32_e32 v193, v193
	s_nop 0
	v_mul_f32_e32 v139, v139, v193
	v_cndmask_b32_e32 v40, v139, v193, vcc
	v_cndmask_b32_e32 v139, v193, v139, vcc
	v_or_b32_e32 v193, s50, v157
	v_cmp_lt_i32_e32 vcc, v193, v130
	s_or_b64 vcc, s[48:49], vcc
	s_nop 0
	v_cndmask_b32_e32 v193, 0, v40, vcc
	v_exp_f32_e64 v40, -|v57|
	v_cndmask_b32_e32 v194, 1.0, v139, vcc
	v_cmp_le_f32_e32 vcc, 0, v57
	v_add_f32_e32 v139, 1.0, v40
	v_rcp_f32_e32 v139, v139
	s_nop 0
	v_mul_f32_e32 v40, v40, v139
	v_cndmask_b32_e32 v57, v40, v139, vcc
	v_cndmask_b32_e32 v139, v139, v40, vcc
	v_or_b32_e32 v40, s50, v158
	v_cmp_lt_i32_e32 vcc, v40, v130
	s_or_b64 vcc, s[48:49], vcc
	s_nop 0
	v_cndmask_b32_e32 v40, 0, v57, vcc
	v_cndmask_b32_e32 v57, 1.0, v139, vcc
	v_exp_f32_e64 v139, -|v41|
	v_cmp_le_f32_e32 vcc, 0, v41
	v_add_f32_e32 v195, 1.0, v139
	v_rcp_f32_e32 v195, v195
	s_nop 0
	v_mul_f32_e32 v139, v139, v195
	v_cndmask_b32_e32 v41, v139, v195, vcc
	v_cndmask_b32_e32 v139, v195, v139, vcc
	v_or_b32_e32 v195, s50, v159
	v_cmp_lt_i32_e32 vcc, v195, v130
	s_or_b64 vcc, s[48:49], vcc
	s_nop 0
	v_cndmask_b32_e32 v195, 0, v41, vcc
	v_exp_f32_e64 v41, -|v58|
	v_cndmask_b32_e32 v196, 1.0, v139, vcc
	v_cmp_le_f32_e32 vcc, 0, v58
	v_add_f32_e32 v139, 1.0, v41
	v_rcp_f32_e32 v139, v139
	s_nop 0
	v_mul_f32_e32 v41, v41, v139
	v_cndmask_b32_e32 v58, v41, v139, vcc
	v_cndmask_b32_e32 v139, v139, v41, vcc
	v_or_b32_e32 v41, s50, v160
	v_cmp_lt_i32_e32 vcc, v41, v130
	s_or_b64 vcc, s[48:49], vcc
	s_nop 0
	v_cndmask_b32_e32 v41, 0, v58, vcc
	v_cndmask_b32_e32 v58, 1.0, v139, vcc
	v_exp_f32_e64 v139, -|v42|
	v_cmp_le_f32_e32 vcc, 0, v42
	v_add_f32_e32 v197, 1.0, v139
	v_rcp_f32_e32 v197, v197
	s_nop 0
	v_mul_f32_e32 v139, v139, v197
	v_cndmask_b32_e32 v42, v139, v197, vcc
	v_cndmask_b32_e32 v139, v197, v139, vcc
	v_or_b32_e32 v197, s50, v161
	v_cmp_lt_i32_e32 vcc, v197, v130
	s_or_b64 vcc, s[48:49], vcc
	s_nop 0
	v_cndmask_b32_e32 v197, 0, v42, vcc
	v_exp_f32_e64 v42, -|v59|
	v_cndmask_b32_e32 v139, 1.0, v139, vcc
	v_cmp_le_f32_e32 vcc, 0, v59
	v_add_f32_e32 v198, 1.0, v42
	v_rcp_f32_e32 v198, v198
	s_nop 0
	v_mul_f32_e32 v42, v42, v198
	v_cndmask_b32_e32 v59, v42, v198, vcc
	v_cndmask_b32_e32 v198, v198, v42, vcc
	v_or_b32_e32 v42, s50, v162
	v_cmp_lt_i32_e32 vcc, v42, v130
	s_or_b64 vcc, s[48:49], vcc
	s_nop 0
	v_cndmask_b32_e32 v42, 0, v59, vcc
	v_cndmask_b32_e32 v59, 1.0, v198, vcc
	v_exp_f32_e64 v198, -|v43|
	v_cmp_le_f32_e32 vcc, 0, v43
	v_add_f32_e32 v199, 1.0, v198
	v_rcp_f32_e32 v199, v199
	s_nop 0
	v_mul_f32_e32 v198, v198, v199
	v_cndmask_b32_e32 v43, v198, v199, vcc
	v_cndmask_b32_e32 v199, v199, v198, vcc
	v_or_b32_e32 v198, s50, v163
	v_cmp_lt_i32_e32 vcc, v198, v130
	s_or_b64 vcc, s[48:49], vcc
	s_nop 0
	v_cndmask_b32_e32 v198, 0, v43, vcc
	v_exp_f32_e64 v43, -|v60|
	v_cndmask_b32_e32 v199, 1.0, v199, vcc
	v_cmp_le_f32_e32 vcc, 0, v60
	v_add_f32_e32 v200, 1.0, v43
	v_rcp_f32_e32 v200, v200
	s_nop 0
	v_mul_f32_e32 v43, v43, v200
	v_cndmask_b32_e32 v60, v43, v200, vcc
	v_cndmask_b32_e32 v200, v200, v43, vcc
	v_or_b32_e32 v43, s50, v164
	v_cmp_lt_i32_e32 vcc, v43, v130
	s_or_b64 vcc, s[48:49], vcc
	s_nop 0
	v_cndmask_b32_e32 v43, 0, v60, vcc
	v_cndmask_b32_e32 v60, 1.0, v200, vcc
	v_exp_f32_e64 v200, -|v44|
	v_cmp_le_f32_e32 vcc, 0, v44
	v_add_f32_e32 v201, 1.0, v200
	v_rcp_f32_e32 v201, v201
	s_nop 0
	v_mul_f32_e32 v200, v200, v201
	v_cndmask_b32_e32 v44, v200, v201, vcc
	v_cndmask_b32_e32 v201, v201, v200, vcc
	v_or_b32_e32 v200, s50, v165
	v_cmp_lt_i32_e32 vcc, v200, v130
	s_or_b64 vcc, s[48:49], vcc
	s_nop 0
	v_cndmask_b32_e32 v200, 0, v44, vcc
	v_exp_f32_e64 v44, -|v61|
	v_cndmask_b32_e32 v201, 1.0, v201, vcc
	v_cmp_le_f32_e32 vcc, 0, v61
	v_add_f32_e32 v202, 1.0, v44
	v_rcp_f32_e32 v202, v202
	s_nop 0
	v_mul_f32_e32 v44, v44, v202
	v_cndmask_b32_e32 v61, v44, v202, vcc
; DI float fast_exp2(float x) { return __builtin_amdgcn_exp2f(x); }
; DI int crow(int i, int h) { return (i & 3) + 8 * (i >> 2) + 4 * h; }
; #define AT_PV(f, P, S2) do { const bf16x8 pf_ = pack8(P, S2); o0 = MFMA32(vaf[f][0], pf_, o0); o1 = MFMA32(vaf[f][1], pf_, o1); if (MODE != 1) lacc = MFMA32(ones, pf_, lacc); } while (0)
; template <int MODE>
; DI void attn_unit(unsigned char* ws, int b, int h, int qb, LAS unsigned char* lds, bool do_store = true) {
;     ...
;                 for (int i = 0; i < 16; ++i) {
;                     { const float z = p0[i]; const float e = fast_exp2(-fabsf(z)), rc = __builtin_amdgcn_rcpf(1.f + e), t = e * rc; float bt = z >= 0.f ? rc : t, kp = z >= 0.f ? t : rc;
;                       if (needmask && !(kbase + crow(i, hh) < qg)) { bt = 0.f; kp = 1.f; } p0[i] = bt; k0v[i] = kp; }
;                     { const float z = p1[i]; const float e = fast_exp2(-fabsf(z)), rc = __builtin_amdgcn_rcpf(1.f + e), t = e * rc; float bt = z >= 0.f ? rc : t, kp = z >= 0.f ? t : rc;
;                       if (needmask && !(kbase + 32 + crow(i, hh) < qg)) { bt = 0.f; kp = 1.f; } p1[i] = bt; k1v[i] = kp; }
;                 }
;                 float run = carry;
; #pragma unroll
;                 for (int u = 7; u >= 0; --u) {
;                     const int g = u & 3;
;                     float gs = (u >= 4) ? ((k1v[4 * g] * k1v[4 * g + 1]) * (k1v[4 * g + 2] * k1v[4 * g + 3])) : ((k0v[4 * g] * k0v[4 * g + 1]) * (k0v[4 * g + 2] * k0v[4 * g + 3]));
;                     auto rr = __builtin_amdgcn_permlane32_swap(__float_as_uint(gs), __float_as_uint(gs), false, false);
;                     const float glo = __uint_as_float(rr[0]), ghi = __uint_as_float(rr[1]);
;                     float a = run * (hh == 0 ? ghi : 1.f);
; #pragma unroll
;     ...
;                         if (u >= 4) { const float bt = p1[4 * g + jj]; p1[4 * g + jj] = bt * a; a *= k1v[4 * g + jj]; }
;                         else { const float bt = p0[4 * g + jj]; p0[4 * g + jj] = bt * a; a *= k0v[4 * g + jj]; }
;                     }
;                     run *= glo * ghi;
;                     if (u == 6) AT_PV(3, p1, 1); else if (u == 4) AT_PV(2, p1, 0); else if (u == 2) AT_PV(1, p0, 1); else if (u == 0) AT_PV(0, p0, 0);
	v_cndmask_b32_e32 v202, v202, v44, vcc
	v_or_b32_e32 v44, s50, v166
	v_cmp_lt_i32_e32 vcc, v44, v130
	s_or_b64 vcc, s[48:49], vcc
	s_nop 0
	v_cndmask_b32_e32 v44, 0, v61, vcc
	v_cndmask_b32_e32 v61, 1.0, v202, vcc
	v_exp_f32_e64 v202, -|v45|
	v_cmp_le_f32_e32 vcc, 0, v45
	v_add_f32_e32 v203, 1.0, v202
	v_rcp_f32_e32 v203, v203
	s_nop 0
	v_mul_f32_e32 v202, v202, v203
	v_cndmask_b32_e32 v45, v202, v203, vcc
	v_cndmask_b32_e32 v203, v203, v202, vcc
	v_or_b32_e32 v202, s50, v167
	v_cmp_lt_i32_e32 vcc, v202, v130
	s_or_b64 vcc, s[48:49], vcc
	s_nop 0
	v_cndmask_b32_e32 v202, 0, v45, vcc
	v_exp_f32_e64 v45, -|v62|
	v_cndmask_b32_e32 v203, 1.0, v203, vcc
	v_cmp_le_f32_e32 vcc, 0, v62
	v_add_f32_e32 v204, 1.0, v45
	v_rcp_f32_e32 v204, v204
	s_nop 0
	v_mul_f32_e32 v45, v45, v204
	v_cndmask_b32_e32 v62, v45, v204, vcc
	v_cndmask_b32_e32 v204, v204, v45, vcc
	v_or_b32_e32 v45, s50, v168
	v_cmp_lt_i32_e32 vcc, v45, v130
	s_or_b64 vcc, s[48:49], vcc
	s_nop 0
	v_cndmask_b32_e32 v45, 0, v62, vcc
	v_cndmask_b32_e32 v62, 1.0, v204, vcc
	v_exp_f32_e64 v204, -|v46|
	v_cmp_le_f32_e32 vcc, 0, v46
	v_add_f32_e32 v205, 1.0, v204
	v_rcp_f32_e32 v205, v205
	s_nop 0
	v_mul_f32_e32 v204, v204, v205
	v_cndmask_b32_e32 v46, v204, v205, vcc
	v_cndmask_b32_e32 v204, v205, v204, vcc
	v_or_b32_e32 v205, s50, v169
	v_cmp_lt_i32_e32 vcc, v205, v130
	v_exp_f32_e64 v205, -|v63|
	s_or_b64 vcc, s[48:49], vcc
	v_cndmask_b32_e32 v46, 0, v46, vcc
	v_cndmask_b32_e32 v204, 1.0, v204, vcc
	v_add_f32_e32 v206, 1.0, v205
	v_rcp_f32_e32 v206, v206
	v_cmp_le_f32_e32 vcc, 0, v63
	v_mul_f32_e32 v205, v205, v206
	s_nop 0
	v_cndmask_b32_e32 v63, v205, v206, vcc
	v_cndmask_b32_e32 v205, v206, v205, vcc
	v_or_b32_e32 v206, s50, v170
	v_cmp_lt_i32_e32 vcc, v206, v130
	v_exp_f32_e64 v206, -|v47|
	s_or_b64 vcc, s[48:49], vcc
	v_cndmask_b32_e32 v63, 0, v63, vcc
	v_cndmask_b32_e32 v205, 1.0, v205, vcc
	v_add_f32_e32 v207, 1.0, v206
	v_rcp_f32_e32 v207, v207
	v_cmp_le_f32_e32 vcc, 0, v47
	v_mul_f32_e32 v206, v206, v207
	s_nop 0
	v_cndmask_b32_e32 v47, v206, v207, vcc
	v_cndmask_b32_e32 v206, v207, v206, vcc
	v_or_b32_e32 v207, s50, v171
	v_cmp_lt_i32_e32 vcc, v207, v130
	v_exp_f32_e64 v207, -|v64|
	s_or_b64 vcc, s[48:49], vcc
	v_cndmask_b32_e32 v47, 0, v47, vcc
	v_cndmask_b32_e32 v206, 1.0, v206, vcc
	v_add_f32_e32 v208, 1.0, v207
	v_rcp_f32_e32 v208, v208
	v_cmp_le_f32_e32 vcc, 0, v64
	v_mul_f32_e32 v204, v204, v206
	v_mul_f32_e32 v207, v207, v208
	v_cndmask_b32_e32 v64, v207, v208, vcc
	v_cndmask_b32_e32 v207, v208, v207, vcc
	v_or_b32_e32 v208, s50, v176
	v_cmp_lt_i32_e32 vcc, v208, v130
	s_or_b64 vcc, s[48:49], vcc
	s_nop 0
	v_cndmask_b32_e32 v208, 0, v64, vcc
	v_exp_f32_e64 v64, -|v48|
	v_cndmask_b32_e32 v207, 1.0, v207, vcc
	v_cmp_le_f32_e32 vcc, 0, v48
	v_add_f32_e32 v209, 1.0, v64
	v_rcp_f32_e32 v209, v209
	s_nop 0
	v_mul_f32_e32 v64, v64, v209
	v_cndmask_b32_e32 v48, v64, v209, vcc
	v_cndmask_b32_e32 v64, v209, v64, vcc
	v_or_b32_e32 v209, s50, v177
	v_cmp_lt_i32_e32 vcc, v209, v130
	v_exp_f32_e64 v209, -|v65|
	s_or_b64 vcc, s[48:49], vcc
	v_cndmask_b32_e32 v48, 0, v48, vcc
	v_cndmask_b32_e32 v64, 1.0, v64, vcc
	v_add_f32_e32 v220, 1.0, v209
	v_rcp_f32_e32 v220, v220
	v_cmp_le_f32_e32 vcc, 0, v65
	v_mul_f32_e32 v209, v209, v220
	s_nop 0
	v_cndmask_b32_e32 v65, v209, v220, vcc
	v_cndmask_b32_e32 v209, v220, v209, vcc
	v_or_b32_e32 v220, s50, v178
	v_cmp_lt_i32_e32 vcc, v220, v130
	s_or_b64 vcc, s[48:49], vcc
	s_nop 0
	v_cndmask_b32_e32 v220, 0, v65, vcc
	v_exp_f32_e64 v65, -|v49|
	v_cndmask_b32_e32 v209, 1.0, v209, vcc
	v_cmp_le_f32_e32 vcc, 0, v49
	v_add_f32_e32 v221, 1.0, v65
	v_rcp_f32_e32 v221, v221
	s_nop 0
	v_mul_f32_e32 v65, v65, v221
	v_cndmask_b32_e32 v49, v65, v221, vcc
	v_cndmask_b32_e32 v65, v221, v65, vcc
	v_or_b32_e32 v221, s50, v179
	v_cmp_lt_i32_e32 vcc, v221, v130
	s_or_b64 vcc, s[48:49], vcc
	s_nop 0
	v_cndmask_b32_e32 v65, 1.0, v65, vcc
	v_mul_f32_e32 v221, v64, v65
	v_mul_f32_e32 v204, v204, v221
	v_mov_b32_e32 v221, v204
	s_nop 1
	v_permlane32_swap_b32_e32 v204, v221
	v_cndmask_b32_e64 v222, 1.0, v221, s[44:45]
	v_mul_f32_e32 v222, v138, v222
	v_cndmask_b32_e32 v49, 0, v49, vcc
	v_mul_f32_e32 v65, v65, v222
	v_mul_f32_e32 v49, v49, v222
	v_mul_f32_e32 v222, v48, v65
	v_mul_f32_e32 v48, v64, v65
	v_mul_f32_e32 v223, v47, v48
	v_mul_f32_e32 v47, v206, v48
	v_mul_f32_e32 v48, v46, v47
	v_mul_f32_e32 v47, v139, v199
	v_mul_f32_e32 v64, v201, v203
	v_mul_f32_e32 v139, v47, v64
	v_mov_b32_e32 v47, v139
	v_mul_f32_e32 v46, v204, v221
	s_nop 0
	v_permlane32_swap_b32_e32 v139, v47
	v_cndmask_b32_e64 v64, 1.0, v47, s[44:45]
	v_pk_mul_f32 v[46:47], v[138:139], v[46:47]
	v_cvt_pk_bf16_f32 v48, v48, v223
	v_mul_f32_e32 v64, v46, v64
	v_mul_f32_e32 v138, v202, v64
	v_mul_f32_e32 v64, v203, v64
	v_mul_f32_e32 v139, v200, v64
	v_mul_f32_e32 v64, v201, v64
	v_mul_f32_e32 v198, v198, v64
	v_mul_f32_e32 v64, v199, v64
	v_mul_f32_e32 v197, v197, v64
	v_pk_mul_f32 v[64:65], v[46:47], v[46:47] op_sel:[0,1] op_sel_hi:[1,0]
	v_cvt_pk_bf16_f32 v46, v197, v198
	v_cvt_pk_bf16_f32 v47, v139, v138
	v_cvt_pk_bf16_f32 v49, v222, v49
	v_mul_f32_e32 v65, v186, v188
	s_waitcnt lgkmcnt(2)
; #define AT_PV(f, P, S2) do { const bf16x8 pf_ = pack8(P, S2); o0 = MFMA32(vaf[f][0], pf_, o0); o1 = MFMA32(vaf[f][1], pf_, o1); if (MODE != 1) lacc = MFMA32(ones, pf_, lacc); } while (0)
; template <int MODE>
; DI void attn_unit(unsigned char* ws, int b, int h, int qb, LAS unsigned char* lds, bool do_store = true) {
;     ...
;                 float run = carry;
; #pragma unroll
;                 for (int u = 7; u >= 0; --u) {
;                     const int g = u & 3;
;                     float gs = (u >= 4) ? ((k1v[4 * g] * k1v[4 * g + 1]) * (k1v[4 * g + 2] * k1v[4 * g + 3])) : ((k0v[4 * g] * k0v[4 * g + 1]) * (k0v[4 * g + 2] * k0v[4 * g + 3]));
;                     auto rr = __builtin_amdgcn_permlane32_swap(__float_as_uint(gs), __float_as_uint(gs), false, false);
;                     const float glo = __uint_as_float(rr[0]), ghi = __uint_as_float(rr[1]);
;                     float a = run * (hh == 0 ? ghi : 1.f);
; #pragma unroll
;     ...
;                         if (u >= 4) { const float bt = p1[4 * g + jj]; p1[4 * g + jj] = bt * a; a *= k1v[4 * g + jj]; }
;                         else { const float bt = p0[4 * g + jj]; p0[4 * g + jj] = bt * a; a *= k0v[4 * g + jj]; }
;                     }
;                     run *= glo * ghi;
;                     if (u == 6) AT_PV(3, p1, 1); else if (u == 4) AT_PV(2, p1, 0); else if (u == 2) AT_PV(1, p0, 1); else if (u == 0) AT_PV(0, p0, 0);
;                 }
;                 carry = run;
;                 wfin = __all(carry < 1.2e-38f);
	v_mfma_f32_32x32x16_bf16 v[18:33], v[126:129], v[46:49], v[18:33]
	s_waitcnt lgkmcnt(0)
	v_mfma_f32_32x32x16_bf16 v[2:17], v[122:125], v[46:49], v[2:17]
	v_mul_f32_e32 v46, v190, v192
	v_mul_f32_e32 v47, v194, v196
	v_mul_f32_e32 v46, v46, v47
	v_mov_b32_e32 v47, v46
	s_nop 1
	v_permlane32_swap_b32_e32 v46, v47
	v_cndmask_b32_e64 v48, 1.0, v47, s[44:45]
	v_mul_f32_e32 v46, v46, v47
	v_mul_f32_e32 v47, v182, v184
	v_mul_f32_e32 v65, v47, v65
	v_mov_b32_e32 v47, v65
	s_nop 1
	v_permlane32_swap_b32_e32 v65, v47
	v_cndmask_b32_e64 v124, 1.0, v47, s[44:45]
	v_pk_mul_f32 v[46:47], v[64:65], v[46:47]
	v_mul_f32_e32 v48, v64, v48
	v_mul_f32_e32 v64, v46, v124
	v_mul_f32_e32 v49, v195, v48
	v_mul_f32_e32 v48, v196, v48
	v_mul_f32_e32 v124, v187, v64
	v_mul_f32_e32 v64, v188, v64
	v_mul_f32_e32 v122, v193, v48
	v_mul_f32_e32 v48, v194, v48
	v_mul_f32_e32 v125, v185, v64
	v_mul_f32_e32 v64, v186, v64
	v_mul_f32_e32 v123, v191, v48
	v_mul_f32_e32 v48, v192, v48
	v_mul_f32_e32 v126, v183, v64
	v_mul_f32_e32 v64, v184, v64
	v_mul_f32_e32 v48, v189, v48
	v_mul_f32_e32 v127, v181, v64
	v_pk_mul_f32 v[64:65], v[46:47], v[46:47] op_sel:[0,1] op_sel_hi:[1,0]
	v_cvt_pk_bf16_f32 v46, v127, v126
	v_cvt_pk_bf16_f32 v47, v125, v124
	v_cvt_pk_bf16_f32 v48, v48, v123
	v_cvt_pk_bf16_f32 v49, v122, v49
	s_nop 1
	v_mfma_f32_32x32x16_bf16 v[18:33], v[118:121], v[46:49], v[18:33]
	v_mfma_f32_32x32x16_bf16 v[2:17], v[114:117], v[46:49], v[2:17]
	v_mul_f32_e32 v46, v62, v205
	v_mul_f32_e32 v47, v207, v209
	v_mul_f32_e32 v46, v46, v47
	v_mov_b32_e32 v47, v46
	s_nop 1
	v_permlane32_swap_b32_e32 v46, v47
	v_cndmask_b32_e64 v48, 1.0, v47, s[44:45]
	v_mul_f32_e32 v48, v64, v48
	v_mul_f32_e32 v49, v220, v48
	v_mul_f32_e32 v48, v209, v48
	v_mul_f32_e32 v62, v208, v48
	v_mul_f32_e32 v48, v207, v48
	v_mul_f32_e32 v63, v63, v48
	v_mul_f32_e32 v48, v205, v48
	v_mul_f32_e32 v45, v45, v48
	v_mul_f32_e32 v46, v46, v47
	v_mul_f32_e32 v47, v58, v59
	v_mul_f32_e32 v48, v60, v61
	v_mul_f32_e32 v65, v47, v48
	v_mov_b32_e32 v47, v65
	s_nop 1
	v_permlane32_swap_b32_e32 v65, v47
	v_cndmask_b32_e64 v48, 1.0, v47, s[44:45]
	v_pk_mul_f32 v[46:47], v[64:65], v[46:47]
	s_nop 0
	v_mul_f32_e32 v48, v46, v48
	v_mul_f32_e32 v44, v44, v48
	v_mul_f32_e32 v48, v61, v48
	v_mul_f32_e32 v43, v43, v48
	v_mul_f32_e32 v48, v60, v48
	v_mul_f32_e32 v42, v42, v48
	v_mul_f32_e32 v48, v59, v48
	v_mul_f32_e32 v41, v41, v48
	v_cvt_pk_bf16_f32 v42, v41, v42
	v_cvt_pk_bf16_f32 v43, v43, v44
	v_cvt_pk_bf16_f32 v44, v45, v63
	v_cvt_pk_bf16_f32 v45, v62, v49
	v_mul_f32_e32 v41, v54, v55
	v_pk_mul_f32 v[46:47], v[46:47], v[46:47] op_sel:[0,1] op_sel_hi:[1,0]
	v_mfma_f32_32x32x16_bf16 v[18:33], v[110:113], v[42:45], v[18:33]
	v_mfma_f32_32x32x16_bf16 v[2:17], v[106:109], v[42:45], v[2:17]
	v_mul_f32_e32 v42, v56, v57
	v_mul_f32_e32 v41, v41, v42
	v_mov_b32_e32 v42, v41
	s_nop 1
	v_permlane32_swap_b32_e32 v41, v42
	v_cndmask_b32_e64 v43, 1.0, v42, s[44:45]
	v_mul_f32_e32 v43, v46, v43
	v_mul_f32_e32 v40, v40, v43
	v_mul_f32_e32 v43, v57, v43
	v_mul_f32_e32 v44, v39, v43
	v_mul_f32_e32 v39, v56, v43
	v_mul_f32_e32 v43, v38, v39
	v_mul_f32_e32 v38, v55, v39
	v_mul_f32_e32 v37, v37, v38
	v_mul_f32_e32 v38, v41, v42
	v_mul_f32_e32 v39, v180, v51
	v_mul_f32_e32 v41, v52, v53
	v_mul_f32_e32 v47, v39, v41
	v_mov_b32_e32 v39, v47
	s_nop 1
	v_permlane32_swap_b32_e32 v47, v39
	v_cndmask_b32_e64 v41, 1.0, v39, s[44:45]
	v_pk_mul_f32 v[38:39], v[46:47], v[38:39]
	s_nop 0
	v_mul_f32_e32 v41, v38, v41
	v_mul_f32_e32 v36, v36, v41
	v_mul_f32_e32 v41, v53, v41
	v_mul_f32_e32 v35, v35, v41
	v_mul_f32_e32 v41, v52, v41
	v_mul_f32_e32 v34, v34, v41
	v_mul_f32_e32 v41, v51, v41
	v_mul_f32_e32 v41, v50, v41
	v_cvt_pk_bf16_f32 v34, v41, v34
	v_cvt_pk_bf16_f32 v35, v35, v36
	v_cvt_pk_bf16_f32 v36, v37, v43
	v_cvt_pk_bf16_f32 v37, v44, v40
	v_mul_f32_e32 v138, v38, v39
	v_cmp_gt_f32_e32 vcc, s94, v138
	v_mfma_f32_32x32x16_bf16 v[18:33], v[102:105], v[34:37], v[18:33]
	s_cmp_eq_u64 vcc, exec
	s_cselect_b64 s[48:49], -1, 0
	v_mfma_f32_32x32x16_bf16 v[2:17], v[98:101], v[34:37], v[2:17]

; #define LAS __attribute__((address_space(3)))
; template <int MODE>
; DI void attn_unit(unsigned char* ws, int b, int h, int qb, LAS unsigned char* lds, bool do_store = true) {
;     ...
;         if (kt >= 2) AT_LOADG(kt - 2, half);
;         if (kt * 64 <= qmax_w && !wfin) {
;             const LAS unsigned char* kb = lds + (half ? AT_K1 : AT_K0) + r * KP + hh * 16;
;             f32x16 p0, p1;
; #pragma unroll
;             for (int s = 0; s < NS; ++s) {
;                 const bf16x8 k0 = *(const LAS bf16x8*)(kb + s * 32), k1 = *(const LAS bf16x8*)(kb + 32 * KP + s * 32);
;                 if (s == 0) { p0 = MFMA32(k0, qf[s], zero16); p1 = MFMA32(k1, qf[s], zero16); }
;                 else { p0 = MFMA32(k0, qf[s], p0); p1 = MFMA32(k1, qf[s], p1); }
;             }
;             if (MODE != 1) {
;                 bf16x8 qe = qx;
;                 if (MODE == 2) { const int nbk = kt >> 2; const bool dead = (nbk < qb) && !((mysel >> nbk) & 1u); qe = dead ? qbig : qx; }
;                 p0 = MFMA32(kx, qe, p0); p1 = MFMA32(kx, qe, p1);
;             }
;             bf16x8 vaf[4][2];
;             { const LAS unsigned char* vb = lds + (half ? AT_V1 : AT_V0) + voff;
; #pragma unroll
;               for (int f = 0; f < 4; ++f) { const LAS unsigned char* vp = vb + (16 * f) * VP;
;                   { const s16x4 lo = tr_read(vp), hi = tr_read(vp + 8 * VP); vaf[f][0] = __builtin_shufflevector(lo, hi, 0, 1, 2, 3, 4, 5, 6, 7); }
;                   { const s16x4 lo = tr_read(vp + 64), hi = tr_read(vp + 8 * VP + 64); vaf[f][1] = __builtin_shufflevector(lo, hi, 0, 1, 2, 3, 4, 5, 6, 7); } } }
;     ...
;             const bool needmask = (kt * 64 + 63 >= qmin_w);
;             const int kbase = kt * 64;
;             if (MODE == 1) {
;                 f32x16 k0v, k1v;
; #pragma unroll
;                 for (int i = 0; i < 16; ++i) {
;                     { const float z = p0[i]; const float e = fast_exp2(-fabsf(z)), rc = __builtin_amdgcn_rcpf(1.f + e), t = e * rc; float bt = z >= 0.f ? rc : t, kp = z >= 0.f ? t : rc;
;                       if (needmask && !(kbase + crow(i, hh) < qg)) { bt = 0.f; kp = 1.f; } p0[i] = bt; k0v[i] = kp; }
;                     { const float z = p1[i]; const float e = fast_exp2(-fabsf(z)), rc = __builtin_amdgcn_rcpf(1.f + e), t = e * rc; float bt = z >= 0.f ? rc : t, kp = z >= 0.f ? t : rc;
.LBB0_120:
	v_add_u32_e32 v106, v140, v0
	ds_read_b128 v[34:37], v106 offset:20992
	ds_read_b128 v[38:41], v106 offset:16384
	ds_read_b128 v[98:101], v106 offset:16416
	ds_read_b128 v[102:105], v106 offset:21024
	s_or_b32 s2, s50, 63
	s_cmp_lt_i32 s2, s30
	s_waitcnt lgkmcnt(2)
	v_mfma_f32_32x32x16_bf16 v[50:65], v[38:41], v[74:77], 0
	s_cselect_b64 s[48:49], -1, 0
	v_add_u32_e32 v124, v152, v141
	v_mfma_f32_32x32x16_bf16 v[34:49], v[34:37], v[74:77], 0
	s_waitcnt lgkmcnt(1)
	v_mfma_f32_32x32x16_bf16 v[50:65], v[98:101], v[78:81], v[50:65]
	s_waitcnt lgkmcnt(0)
	v_mfma_f32_32x32x16_bf16 v[34:49], v[102:105], v[78:81], v[34:49]
	ds_read_b128 v[98:101], v106 offset:21056
	ds_read_b128 v[102:105], v106 offset:16448
	s_waitcnt lgkmcnt(0)
	v_mfma_f32_32x32x16_bf16 v[50:65], v[102:105], v[82:85], v[50:65]
	v_mfma_f32_32x32x16_bf16 v[34:49], v[98:101], v[82:85], v[34:49]
	ds_read_b128 v[98:101], v106 offset:21088
	ds_read_b128 v[102:105], v106 offset:16480
	s_waitcnt lgkmcnt(0)
	v_mfma_f32_32x32x16_bf16 v[50:65], v[102:105], v[86:89], v[50:65]
	v_mfma_f32_32x32x16_bf16 v[34:49], v[98:101], v[86:89], v[34:49]
	s_nop 10
	v_exp_f32_e64 v139, -|v50|
	v_cmp_le_f32_e32 vcc, 0, v50
	ds_read_b64_tr_b16 v[102:103], v124 offset:49152
	ds_read_b64_tr_b16 v[104:105], v124 offset:50688
	ds_read_b64_tr_b16 v[98:99], v124 offset:49216
	ds_read_b64_tr_b16 v[100:101], v124 offset:50752
	ds_read_b64_tr_b16 v[110:111], v124 offset:52224
	ds_read_b64_tr_b16 v[112:113], v124 offset:53760
	ds_read_b64_tr_b16 v[106:107], v124 offset:52288
	ds_read_b64_tr_b16 v[108:109], v124 offset:53824
	ds_read_b64_tr_b16 v[118:119], v124 offset:55296
	ds_read_b64_tr_b16 v[120:121], v124 offset:56832
	ds_read_b64_tr_b16 v[114:115], v124 offset:55360
	ds_read_b64_tr_b16 v[116:117], v124 offset:56896
	ds_read_b64_tr_b16 v[126:127], v124 offset:58368
	ds_read_b64_tr_b16 v[128:129], v124 offset:59904
	ds_read_b64_tr_b16 v[122:123], v124 offset:58432
	ds_read_b64_tr_b16 v[124:125], v124 offset:59968
	v_add_f32_e32 v180, 1.0, v139
	v_rcp_f32_e32 v180, v180
	s_nop 0
	v_mul_f32_e32 v139, v139, v180
	v_cndmask_b32_e32 v50, v139, v180, vcc
	v_cndmask_b32_e32 v139, v180, v139, vcc
	v_or_b32_e32 v180, s50, v131
	v_cmp_lt_i32_e32 vcc, v180, v130
	s_or_b64 vcc, s[48:49], vcc
	s_nop 0
	v_cndmask_b32_e32 v180, 1.0, v139, vcc
	v_exp_f32_e64 v139, -|v34|
	v_cndmask_b32_e32 v50, 0, v50, vcc
	v_cmp_le_f32_e32 vcc, 0, v34
	v_add_f32_e32 v181, 1.0, v139
	v_rcp_f32_e32 v181, v181
	s_nop 0
	v_mul_f32_e32 v139, v139, v181
	v_cndmask_b32_e32 v34, v139, v181, vcc
	v_cndmask_b32_e32 v139, v181, v139, vcc
	v_or_b32_e32 v181, s50, v142
	v_cmp_lt_i32_e32 vcc, v181, v130
	s_or_b64 vcc, s[48:49], vcc
	s_nop 0
	v_cndmask_b32_e32 v181, 0, v34, vcc
	v_exp_f32_e64 v34, -|v51|
	v_cndmask_b32_e32 v182, 1.0, v139, vcc
	v_cmp_le_f32_e32 vcc, 0, v51
	v_add_f32_e32 v139, 1.0, v34
	v_rcp_f32_e32 v139, v139
	s_nop 0
	v_mul_f32_e32 v34, v34, v139
	v_cndmask_b32_e32 v51, v34, v139, vcc
	v_cndmask_b32_e32 v139, v139, v34, vcc
	v_or_b32_e32 v34, s50, v143
	v_cmp_lt_i32_e32 vcc, v34, v130
	s_or_b64 vcc, s[48:49], vcc
	s_nop 0
	v_cndmask_b32_e32 v34, 0, v51, vcc
	v_cndmask_b32_e32 v51, 1.0, v139, vcc
	v_exp_f32_e64 v139, -|v35|
	v_cmp_le_f32_e32 vcc, 0, v35
	v_add_f32_e32 v183, 1.0, v139
	v_rcp_f32_e32 v183, v183
	s_nop 0
	v_mul_f32_e32 v139, v139, v183
	v_cndmask_b32_e32 v35, v139, v183, vcc
	v_cndmask_b32_e32 v139, v183, v139, vcc
	v_or_b32_e32 v183, s50, v144
	v_cmp_lt_i32_e32 vcc, v183, v130
	s_or_b64 vcc, s[48:49], vcc
	s_nop 0
	v_cndmask_b32_e32 v183, 0, v35, vcc
	v_exp_f32_e64 v35, -|v52|
	v_cndmask_b32_e32 v184, 1.0, v139, vcc
	v_cmp_le_f32_e32 vcc, 0, v52
	v_add_f32_e32 v139, 1.0, v35
	v_rcp_f32_e32 v139, v139
	s_nop 0
	v_mul_f32_e32 v35, v35, v139
	v_cndmask_b32_e32 v52, v35, v139, vcc
	v_cndmask_b32_e32 v139, v139, v35, vcc
	v_or_b32_e32 v35, s50, v145
	v_cmp_lt_i32_e32 vcc, v35, v130
	s_or_b64 vcc, s[48:49], vcc
	s_nop 0
	v_cndmask_b32_e32 v35, 0, v52, vcc
	v_cndmask_b32_e32 v52, 1.0, v139, vcc
	v_exp_f32_e64 v139, -|v36|
	v_cmp_le_f32_e32 vcc, 0, v36
	v_add_f32_e32 v185, 1.0, v139
	v_rcp_f32_e32 v185, v185
	s_nop 0
	v_mul_f32_e32 v139, v139, v185
	v_cndmask_b32_e32 v36, v139, v185, vcc
	v_cndmask_b32_e32 v139, v185, v139, vcc
	v_or_b32_e32 v185, s50, v146
	v_cmp_lt_i32_e32 vcc, v185, v130
	s_or_b64 vcc, s[48:49], vcc
	s_nop 0
	v_cndmask_b32_e32 v185, 0, v36, vcc
	v_exp_f32_e64 v36, -|v53|
	v_cndmask_b32_e32 v186, 1.0, v139, vcc
	v_cmp_le_f32_e32 vcc, 0, v53
	v_add_f32_e32 v139, 1.0, v36
	v_rcp_f32_e32 v139, v139
	s_nop 0
	v_mul_f32_e32 v36, v36, v139
	v_cndmask_b32_e32 v53, v36, v139, vcc
	v_cndmask_b32_e32 v139, v139, v36, vcc
	v_or_b32_e32 v36, s50, v147
	v_cmp_lt_i32_e32 vcc, v36, v130
	s_or_b64 vcc, s[48:49], vcc
	s_nop 0
	v_cndmask_b32_e32 v36, 0, v53, vcc
	v_cndmask_b32_e32 v53, 1.0, v139, vcc
	v_exp_f32_e64 v139, -|v37|
	v_cmp_le_f32_e32 vcc, 0, v37
	v_add_f32_e32 v187, 1.0, v139
	v_rcp_f32_e32 v187, v187
	s_nop 0
	v_mul_f32_e32 v139, v139, v187
	v_cndmask_b32_e32 v37, v139, v187, vcc
	v_cndmask_b32_e32 v139, v187, v139, vcc
	v_or_b32_e32 v187, s50, v148
	v_cmp_lt_i32_e32 vcc, v187, v130
	s_or_b64 vcc, s[48:49], vcc
	s_nop 0
	v_cndmask_b32_e32 v187, 0, v37, vcc
	v_exp_f32_e64 v37, -|v54|
	v_cndmask_b32_e32 v188, 1.0, v139, vcc
	v_cmp_le_f32_e32 vcc, 0, v54
	v_add_f32_e32 v139, 1.0, v37
	v_rcp_f32_e32 v139, v139
	s_nop 0
	v_mul_f32_e32 v37, v37, v139
	v_cndmask_b32_e32 v54, v37, v139, vcc
	v_cndmask_b32_e32 v139, v139, v37, vcc
	v_or_b32_e32 v37, s50, v149
	v_cmp_lt_i32_e32 vcc, v37, v130
	s_or_b64 vcc, s[48:49], vcc
	s_nop 0
	v_cndmask_b32_e32 v37, 0, v54, vcc
	v_cndmask_b32_e32 v54, 1.0, v139, vcc
; DI float fast_exp2(float x) { return __builtin_amdgcn_exp2f(x); }
; DI int crow(int i, int h) { return (i & 3) + 8 * (i >> 2) + 4 * h; }
; template <int MODE>
; DI void attn_unit(unsigned char* ws, int b, int h, int qb, LAS unsigned char* lds, bool do_store = true) {
;     ...
;                 for (int i = 0; i < 16; ++i) {
;                     { const float z = p0[i]; const float e = fast_exp2(-fabsf(z)), rc = __builtin_amdgcn_rcpf(1.f + e), t = e * rc; float bt = z >= 0.f ? rc : t, kp = z >= 0.f ? t : rc;
;                       if (needmask && !(kbase + crow(i, hh) < qg)) { bt = 0.f; kp = 1.f; } p0[i] = bt; k0v[i] = kp; }
;                     { const float z = p1[i]; const float e = fast_exp2(-fabsf(z)), rc = __builtin_amdgcn_rcpf(1.f + e), t = e * rc; float bt = z >= 0.f ? rc : t, kp = z >= 0.f ? t : rc;
;                       if (needmask && !(kbase + 32 + crow(i, hh) < qg)) { bt = 0.f; kp = 1.f; } p1[i] = bt; k1v[i] = kp; }
;                 }
	v_exp_f32_e64 v139, -|v38|
	v_cmp_le_f32_e32 vcc, 0, v38
	v_add_f32_e32 v189, 1.0, v139
	v_rcp_f32_e32 v189, v189
	s_nop 0
	v_mul_f32_e32 v139, v139, v189
	v_cndmask_b32_e32 v38, v139, v189, vcc
	v_cndmask_b32_e32 v139, v189, v139, vcc
	v_or_b32_e32 v189, s50, v150
	v_cmp_lt_i32_e32 vcc, v189, v130
	s_or_b64 vcc, s[48:49], vcc
	s_nop 0
	v_cndmask_b32_e32 v189, 0, v38, vcc
	v_exp_f32_e64 v38, -|v55|
	v_cndmask_b32_e32 v190, 1.0, v139, vcc
	v_cmp_le_f32_e32 vcc, 0, v55
	v_add_f32_e32 v139, 1.0, v38
	v_rcp_f32_e32 v139, v139
	s_nop 0
	v_mul_f32_e32 v38, v38, v139
	v_cndmask_b32_e32 v55, v38, v139, vcc
	v_cndmask_b32_e32 v139, v139, v38, vcc
	v_or_b32_e32 v38, s50, v154
	v_cmp_lt_i32_e32 vcc, v38, v130
	s_or_b64 vcc, s[48:49], vcc
	s_nop 0
	v_cndmask_b32_e32 v38, 0, v55, vcc
	v_cndmask_b32_e32 v55, 1.0, v139, vcc
	v_exp_f32_e64 v139, -|v39|
	v_cmp_le_f32_e32 vcc, 0, v39
	v_add_f32_e32 v191, 1.0, v139
	v_rcp_f32_e32 v191, v191
	s_nop 0
	v_mul_f32_e32 v139, v139, v191
	v_cndmask_b32_e32 v39, v139, v191, vcc
	v_cndmask_b32_e32 v139, v191, v139, vcc
	v_or_b32_e32 v191, s50, v155
	v_cmp_lt_i32_e32 vcc, v191, v130
	s_or_b64 vcc, s[48:49], vcc
	s_nop 0
	v_cndmask_b32_e32 v191, 0, v39, vcc
	v_exp_f32_e64 v39, -|v56|
	v_cndmask_b32_e32 v192, 1.0, v139, vcc
	v_cmp_le_f32_e32 vcc, 0, v56
	v_add_f32_e32 v139, 1.0, v39
	v_rcp_f32_e32 v139, v139
	s_nop 0
	v_mul_f32_e32 v39, v39, v139
	v_cndmask_b32_e32 v56, v39, v139, vcc
	v_cndmask_b32_e32 v139, v139, v39, vcc
	v_or_b32_e32 v39, s50, v156
	v_cmp_lt_i32_e32 vcc, v39, v130
	s_or_b64 vcc, s[48:49], vcc
	s_nop 0
	v_cndmask_b32_e32 v39, 0, v56, vcc
	v_cndmask_b32_e32 v56, 1.0, v139, vcc
	v_exp_f32_e64 v139, -|v40|
	v_cmp_le_f32_e32 vcc, 0, v40
	v_add_f32_e32 v193, 1.0, v139
	v_rcp_f32_e32 v193, v193
	s_nop 0
	v_mul_f32_e32 v139, v139, v193
	v_cndmask_b32_e32 v40, v139, v193, vcc
	v_cndmask_b32_e32 v139, v193, v139, vcc
	v_or_b32_e32 v193, s50, v157
	v_cmp_lt_i32_e32 vcc, v193, v130
	s_or_b64 vcc, s[48:49], vcc
	s_nop 0
	v_cndmask_b32_e32 v193, 0, v40, vcc
	v_exp_f32_e64 v40, -|v57|
	v_cndmask_b32_e32 v194, 1.0, v139, vcc
	v_cmp_le_f32_e32 vcc, 0, v57
	v_add_f32_e32 v139, 1.0, v40
	v_rcp_f32_e32 v139, v139
	s_nop 0
	v_mul_f32_e32 v40, v40, v139
	v_cndmask_b32_e32 v57, v40, v139, vcc
	v_cndmask_b32_e32 v139, v139, v40, vcc
	v_or_b32_e32 v40, s50, v158
	v_cmp_lt_i32_e32 vcc, v40, v130
	s_or_b64 vcc, s[48:49], vcc
	s_nop 0
	v_cndmask_b32_e32 v40, 0, v57, vcc
	v_cndmask_b32_e32 v57, 1.0, v139, vcc
	v_exp_f32_e64 v139, -|v41|
	v_cmp_le_f32_e32 vcc, 0, v41
	v_add_f32_e32 v195, 1.0, v139
	v_rcp_f32_e32 v195, v195
	s_nop 0
	v_mul_f32_e32 v139, v139, v195
	v_cndmask_b32_e32 v41, v139, v195, vcc
	v_cndmask_b32_e32 v139, v195, v139, vcc
	v_or_b32_e32 v195, s50, v159
	v_cmp_lt_i32_e32 vcc, v195, v130
	s_or_b64 vcc, s[48:49], vcc
	s_nop 0
	v_cndmask_b32_e32 v195, 0, v41, vcc
	v_exp_f32_e64 v41, -|v58|
	v_cndmask_b32_e32 v196, 1.0, v139, vcc
	v_cmp_le_f32_e32 vcc, 0, v58
	v_add_f32_e32 v139, 1.0, v41
	v_rcp_f32_e32 v139, v139
	s_nop 0
	v_mul_f32_e32 v41, v41, v139
	v_cndmask_b32_e32 v58, v41, v139, vcc
	v_cndmask_b32_e32 v139, v139, v41, vcc
	v_or_b32_e32 v41, s50, v160
	v_cmp_lt_i32_e32 vcc, v41, v130
	s_or_b64 vcc, s[48:49], vcc
	s_nop 0
	v_cndmask_b32_e32 v41, 0, v58, vcc
	v_cndmask_b32_e32 v58, 1.0, v139, vcc
	v_exp_f32_e64 v139, -|v42|
	v_cmp_le_f32_e32 vcc, 0, v42
	v_add_f32_e32 v197, 1.0, v139
	v_rcp_f32_e32 v197, v197
	s_nop 0
	v_mul_f32_e32 v139, v139, v197
	v_cndmask_b32_e32 v42, v139, v197, vcc
	v_cndmask_b32_e32 v139, v197, v139, vcc
	v_or_b32_e32 v197, s50, v161
	v_cmp_lt_i32_e32 vcc, v197, v130
	s_or_b64 vcc, s[48:49], vcc
	s_nop 0
	v_cndmask_b32_e32 v197, 0, v42, vcc
	v_exp_f32_e64 v42, -|v59|
	v_cndmask_b32_e32 v139, 1.0, v139, vcc
	v_cmp_le_f32_e32 vcc, 0, v59
	v_add_f32_e32 v198, 1.0, v42
	v_rcp_f32_e32 v198, v198
	s_nop 0
	v_mul_f32_e32 v42, v42, v198
	v_cndmask_b32_e32 v59, v42, v198, vcc
	v_cndmask_b32_e32 v198, v198, v42, vcc
	v_or_b32_e32 v42, s50, v162
	v_cmp_lt_i32_e32 vcc, v42, v130
	s_or_b64 vcc, s[48:49], vcc
	s_nop 0
	v_cndmask_b32_e32 v42, 0, v59, vcc
	v_cndmask_b32_e32 v59, 1.0, v198, vcc
	v_exp_f32_e64 v198, -|v43|
	v_cmp_le_f32_e32 vcc, 0, v43
	v_add_f32_e32 v199, 1.0, v198
	v_rcp_f32_e32 v199, v199
	s_nop 0
	v_mul_f32_e32 v198, v198, v199
	v_cndmask_b32_e32 v43, v198, v199, vcc
	v_cndmask_b32_e32 v199, v199, v198, vcc
	v_or_b32_e32 v198, s50, v163
	v_cmp_lt_i32_e32 vcc, v198, v130
	s_or_b64 vcc, s[48:49], vcc
	s_nop 0
	v_cndmask_b32_e32 v198, 0, v43, vcc
	v_exp_f32_e64 v43, -|v60|
	v_cndmask_b32_e32 v199, 1.0, v199, vcc
	v_cmp_le_f32_e32 vcc, 0, v60
	v_add_f32_e32 v200, 1.0, v43
	v_rcp_f32_e32 v200, v200
	s_nop 0
	v_mul_f32_e32 v43, v43, v200
	v_cndmask_b32_e32 v60, v43, v200, vcc
	v_cndmask_b32_e32 v200, v200, v43, vcc
	v_or_b32_e32 v43, s50, v164
	v_cmp_lt_i32_e32 vcc, v43, v130
	s_or_b64 vcc, s[48:49], vcc
	s_nop 0
	v_cndmask_b32_e32 v43, 0, v60, vcc
	v_cndmask_b32_e32 v60, 1.0, v200, vcc
	v_exp_f32_e64 v200, -|v44|
	v_cmp_le_f32_e32 vcc, 0, v44
	v_add_f32_e32 v201, 1.0, v200
	v_rcp_f32_e32 v201, v201
	s_nop 0
	v_mul_f32_e32 v200, v200, v201
	v_cndmask_b32_e32 v44, v200, v201, vcc
	v_cndmask_b32_e32 v201, v201, v200, vcc
	v_or_b32_e32 v200, s50, v165
	v_cmp_lt_i32_e32 vcc, v200, v130
	s_or_b64 vcc, s[48:49], vcc
	s_nop 0
	v_cndmask_b32_e32 v200, 0, v44, vcc
	v_exp_f32_e64 v44, -|v61|
	v_cndmask_b32_e32 v201, 1.0, v201, vcc
	v_cmp_le_f32_e32 vcc, 0, v61
	v_add_f32_e32 v202, 1.0, v44
	v_rcp_f32_e32 v202, v202
	s_nop 0
	v_mul_f32_e32 v44, v44, v202
	v_cndmask_b32_e32 v61, v44, v202, vcc
	v_cndmask_b32_e32 v202, v202, v44, vcc
	v_or_b32_e32 v44, s50, v166
	v_cmp_lt_i32_e32 vcc, v44, v130
; DI float fast_exp2(float x) { return __builtin_amdgcn_exp2f(x); }
; DI int crow(int i, int h) { return (i & 3) + 8 * (i >> 2) + 4 * h; }
; #define AT_PV(f, P, S2) do { const bf16x8 pf_ = pack8(P, S2); o0 = MFMA32(vaf[f][0], pf_, o0); o1 = MFMA32(vaf[f][1], pf_, o1); if (MODE != 1) lacc = MFMA32(ones, pf_, lacc); } while (0)
; template <int MODE>
; DI void attn_unit(unsigned char* ws, int b, int h, int qb, LAS unsigned char* lds, bool do_store = true) {
;     ...
;                 for (int i = 0; i < 16; ++i) {
;                     { const float z = p0[i]; const float e = fast_exp2(-fabsf(z)), rc = __builtin_amdgcn_rcpf(1.f + e), t = e * rc; float bt = z >= 0.f ? rc : t, kp = z >= 0.f ? t : rc;
;                       if (needmask && !(kbase + crow(i, hh) < qg)) { bt = 0.f; kp = 1.f; } p0[i] = bt; k0v[i] = kp; }
;                     { const float z = p1[i]; const float e = fast_exp2(-fabsf(z)), rc = __builtin_amdgcn_rcpf(1.f + e), t = e * rc; float bt = z >= 0.f ? rc : t, kp = z >= 0.f ? t : rc;
;                       if (needmask && !(kbase + 32 + crow(i, hh) < qg)) { bt = 0.f; kp = 1.f; } p1[i] = bt; k1v[i] = kp; }
;                 }
;                 float run = carry;
; #pragma unroll
;                 for (int u = 7; u >= 0; --u) {
;                     const int g = u & 3;
;                     float gs = (u >= 4) ? ((k1v[4 * g] * k1v[4 * g + 1]) * (k1v[4 * g + 2] * k1v[4 * g + 3])) : ((k0v[4 * g] * k0v[4 * g + 1]) * (k0v[4 * g + 2] * k0v[4 * g + 3]));
;                     auto rr = __builtin_amdgcn_permlane32_swap(__float_as_uint(gs), __float_as_uint(gs), false, false);
;                     const float glo = __uint_as_float(rr[0]), ghi = __uint_as_float(rr[1]);
;                     float a = run * (hh == 0 ? ghi : 1.f);
; #pragma unroll
;     ...
;                         if (u >= 4) { const float bt = p1[4 * g + jj]; p1[4 * g + jj] = bt * a; a *= k1v[4 * g + jj]; }
;                         else { const float bt = p0[4 * g + jj]; p0[4 * g + jj] = bt * a; a *= k0v[4 * g + jj]; }
;                     }
;                     run *= glo * ghi;
;                     if (u == 6) AT_PV(3, p1, 1); else if (u == 4) AT_PV(2, p1, 0); else if (u == 2) AT_PV(1, p0, 1); else if (u == 0) AT_PV(0, p0, 0);
	s_or_b64 vcc, s[48:49], vcc
	s_nop 0
	v_cndmask_b32_e32 v44, 0, v61, vcc
	v_cndmask_b32_e32 v61, 1.0, v202, vcc
	v_exp_f32_e64 v202, -|v45|
	v_cmp_le_f32_e32 vcc, 0, v45
	v_add_f32_e32 v203, 1.0, v202
	v_rcp_f32_e32 v203, v203
	s_nop 0
	v_mul_f32_e32 v202, v202, v203
	v_cndmask_b32_e32 v45, v202, v203, vcc
	v_cndmask_b32_e32 v203, v203, v202, vcc
	v_or_b32_e32 v202, s50, v167
	v_cmp_lt_i32_e32 vcc, v202, v130
	s_or_b64 vcc, s[48:49], vcc
	s_nop 0
	v_cndmask_b32_e32 v202, 0, v45, vcc
	v_exp_f32_e64 v45, -|v62|
	v_cndmask_b32_e32 v203, 1.0, v203, vcc
	v_cmp_le_f32_e32 vcc, 0, v62
	v_add_f32_e32 v204, 1.0, v45
	v_rcp_f32_e32 v204, v204
	s_nop 0
	v_mul_f32_e32 v45, v45, v204
	v_cndmask_b32_e32 v62, v45, v204, vcc
	v_cndmask_b32_e32 v204, v204, v45, vcc
	v_or_b32_e32 v45, s50, v168
	v_cmp_lt_i32_e32 vcc, v45, v130
	s_or_b64 vcc, s[48:49], vcc
	s_nop 0
	v_cndmask_b32_e32 v45, 0, v62, vcc
	v_cndmask_b32_e32 v62, 1.0, v204, vcc
	v_exp_f32_e64 v204, -|v46|
	v_cmp_le_f32_e32 vcc, 0, v46
	v_add_f32_e32 v205, 1.0, v204
	v_rcp_f32_e32 v205, v205
	s_nop 0
	v_mul_f32_e32 v204, v204, v205
	v_cndmask_b32_e32 v46, v204, v205, vcc
	v_cndmask_b32_e32 v204, v205, v204, vcc
	v_or_b32_e32 v205, s50, v169
	v_cmp_lt_i32_e32 vcc, v205, v130
	v_exp_f32_e64 v205, -|v63|
	s_or_b64 vcc, s[48:49], vcc
	v_cndmask_b32_e32 v46, 0, v46, vcc
	v_cndmask_b32_e32 v204, 1.0, v204, vcc
	v_add_f32_e32 v206, 1.0, v205
	v_rcp_f32_e32 v206, v206
	v_cmp_le_f32_e32 vcc, 0, v63
	v_mul_f32_e32 v205, v205, v206
	s_nop 0
	v_cndmask_b32_e32 v63, v205, v206, vcc
	v_cndmask_b32_e32 v205, v206, v205, vcc
	v_or_b32_e32 v206, s50, v170
	v_cmp_lt_i32_e32 vcc, v206, v130
	v_exp_f32_e64 v206, -|v47|
	s_or_b64 vcc, s[48:49], vcc
	v_cndmask_b32_e32 v63, 0, v63, vcc
	v_cndmask_b32_e32 v205, 1.0, v205, vcc
	v_add_f32_e32 v207, 1.0, v206
	v_rcp_f32_e32 v207, v207
	v_cmp_le_f32_e32 vcc, 0, v47
	v_mul_f32_e32 v206, v206, v207
	s_nop 0
	v_cndmask_b32_e32 v47, v206, v207, vcc
	v_cndmask_b32_e32 v206, v207, v206, vcc
	v_or_b32_e32 v207, s50, v171
	v_cmp_lt_i32_e32 vcc, v207, v130
	v_exp_f32_e64 v207, -|v64|
	s_or_b64 vcc, s[48:49], vcc
	v_cndmask_b32_e32 v47, 0, v47, vcc
	v_cndmask_b32_e32 v206, 1.0, v206, vcc
	v_add_f32_e32 v208, 1.0, v207
	v_rcp_f32_e32 v208, v208
	v_cmp_le_f32_e32 vcc, 0, v64
	v_mul_f32_e32 v204, v204, v206
	v_mul_f32_e32 v207, v207, v208
	v_cndmask_b32_e32 v64, v207, v208, vcc
	v_cndmask_b32_e32 v207, v208, v207, vcc
	v_or_b32_e32 v208, s50, v176
	v_cmp_lt_i32_e32 vcc, v208, v130
	s_or_b64 vcc, s[48:49], vcc
	s_nop 0
	v_cndmask_b32_e32 v208, 0, v64, vcc
	v_exp_f32_e64 v64, -|v48|
	v_cndmask_b32_e32 v207, 1.0, v207, vcc
	v_cmp_le_f32_e32 vcc, 0, v48
	v_add_f32_e32 v209, 1.0, v64
	v_rcp_f32_e32 v209, v209
	s_nop 0
	v_mul_f32_e32 v64, v64, v209
	v_cndmask_b32_e32 v48, v64, v209, vcc
	v_cndmask_b32_e32 v64, v209, v64, vcc
	v_or_b32_e32 v209, s50, v177
	v_cmp_lt_i32_e32 vcc, v209, v130
	v_exp_f32_e64 v209, -|v65|
	s_or_b64 vcc, s[48:49], vcc
	v_cndmask_b32_e32 v48, 0, v48, vcc
	v_cndmask_b32_e32 v64, 1.0, v64, vcc
	v_add_f32_e32 v220, 1.0, v209
	v_rcp_f32_e32 v220, v220
	v_cmp_le_f32_e32 vcc, 0, v65
	v_mul_f32_e32 v209, v209, v220
	s_nop 0
	v_cndmask_b32_e32 v65, v209, v220, vcc
	v_cndmask_b32_e32 v209, v220, v209, vcc
	v_or_b32_e32 v220, s50, v178
	v_cmp_lt_i32_e32 vcc, v220, v130
	s_or_b64 vcc, s[48:49], vcc
	s_nop 0
	v_cndmask_b32_e32 v220, 0, v65, vcc
	v_exp_f32_e64 v65, -|v49|
	v_cndmask_b32_e32 v209, 1.0, v209, vcc
	v_cmp_le_f32_e32 vcc, 0, v49
	v_add_f32_e32 v221, 1.0, v65
	v_rcp_f32_e32 v221, v221
	s_nop 0
	v_mul_f32_e32 v65, v65, v221
	v_cndmask_b32_e32 v49, v65, v221, vcc
	v_cndmask_b32_e32 v65, v221, v65, vcc
	v_or_b32_e32 v221, s50, v179
	v_cmp_lt_i32_e32 vcc, v221, v130
	s_or_b64 vcc, s[48:49], vcc
	s_nop 0
	v_cndmask_b32_e32 v65, 1.0, v65, vcc
	v_mul_f32_e32 v221, v64, v65
	v_mul_f32_e32 v204, v204, v221
	v_mov_b32_e32 v221, v204
	s_nop 1
	v_permlane32_swap_b32_e32 v204, v221
	v_cndmask_b32_e64 v222, 1.0, v221, s[44:45]
	v_mul_f32_e32 v222, v138, v222
	v_cndmask_b32_e32 v49, 0, v49, vcc
	v_mul_f32_e32 v65, v65, v222
	v_mul_f32_e32 v49, v49, v222
	v_mul_f32_e32 v222, v48, v65
	v_mul_f32_e32 v48, v64, v65
	v_mul_f32_e32 v223, v47, v48
	v_mul_f32_e32 v47, v206, v48
	v_mul_f32_e32 v48, v46, v47
	v_mul_f32_e32 v47, v139, v199
	v_mul_f32_e32 v64, v201, v203
	v_mul_f32_e32 v139, v47, v64
	v_mov_b32_e32 v47, v139
	v_mul_f32_e32 v46, v204, v221
	s_nop 0
	v_permlane32_swap_b32_e32 v139, v47
	v_cndmask_b32_e64 v64, 1.0, v47, s[44:45]
	v_pk_mul_f32 v[46:47], v[138:139], v[46:47]
	v_cvt_pk_bf16_f32 v48, v48, v223
	v_mul_f32_e32 v64, v46, v64
	v_mul_f32_e32 v138, v202, v64
	v_mul_f32_e32 v64, v203, v64
	v_mul_f32_e32 v139, v200, v64
	v_mul_f32_e32 v64, v201, v64
	v_mul_f32_e32 v198, v198, v64
	v_mul_f32_e32 v64, v199, v64
	v_mul_f32_e32 v197, v197, v64
	v_pk_mul_f32 v[64:65], v[46:47], v[46:47] op_sel:[0,1] op_sel_hi:[1,0]
	v_cvt_pk_bf16_f32 v46, v197, v198
	v_cvt_pk_bf16_f32 v47, v139, v138
	v_cvt_pk_bf16_f32 v49, v222, v49
	v_mul_f32_e32 v65, v186, v188
	s_waitcnt lgkmcnt(2)
; #define AT_PV(f, P, S2) do { const bf16x8 pf_ = pack8(P, S2); o0 = MFMA32(vaf[f][0], pf_, o0); o1 = MFMA32(vaf[f][1], pf_, o1); if (MODE != 1) lacc = MFMA32(ones, pf_, lacc); } while (0)
; template <int MODE>
; DI void attn_unit(unsigned char* ws, int b, int h, int qb, LAS unsigned char* lds, bool do_store = true) {
;     ...
;                 float run = carry;
; #pragma unroll
;                 for (int u = 7; u >= 0; --u) {
;                     const int g = u & 3;
;                     float gs = (u >= 4) ? ((k1v[4 * g] * k1v[4 * g + 1]) * (k1v[4 * g + 2] * k1v[4 * g + 3])) : ((k0v[4 * g] * k0v[4 * g + 1]) * (k0v[4 * g + 2] * k0v[4 * g + 3]));
;                     auto rr = __builtin_amdgcn_permlane32_swap(__float_as_uint(gs), __float_as_uint(gs), false, false);
;                     const float glo = __uint_as_float(rr[0]), ghi = __uint_as_float(rr[1]);
;                     float a = run * (hh == 0 ? ghi : 1.f);
; #pragma unroll
;     ...
;                         if (u >= 4) { const float bt = p1[4 * g + jj]; p1[4 * g + jj] = bt * a; a *= k1v[4 * g + jj]; }
;                         else { const float bt = p0[4 * g + jj]; p0[4 * g + jj] = bt * a; a *= k0v[4 * g + jj]; }
;                     }
;                     run *= glo * ghi;
;                     if (u == 6) AT_PV(3, p1, 1); else if (u == 4) AT_PV(2, p1, 0); else if (u == 2) AT_PV(1, p0, 1); else if (u == 0) AT_PV(0, p0, 0);
;                 }
;                 carry = run;
;                 wfin = __all(carry < 1.2e-38f);
	v_mfma_f32_32x32x16_bf16 v[18:33], v[126:129], v[46:49], v[18:33]
	s_waitcnt lgkmcnt(0)
	v_mfma_f32_32x32x16_bf16 v[2:17], v[122:125], v[46:49], v[2:17]
	v_mul_f32_e32 v46, v190, v192
	v_mul_f32_e32 v47, v194, v196
	v_mul_f32_e32 v46, v46, v47
	v_mov_b32_e32 v47, v46
	s_nop 1
	v_permlane32_swap_b32_e32 v46, v47
	v_cndmask_b32_e64 v48, 1.0, v47, s[44:45]
	v_mul_f32_e32 v46, v46, v47
	v_mul_f32_e32 v47, v182, v184
	v_mul_f32_e32 v65, v47, v65
	v_mov_b32_e32 v47, v65
	s_nop 1
	v_permlane32_swap_b32_e32 v65, v47
	v_cndmask_b32_e64 v124, 1.0, v47, s[44:45]
	v_pk_mul_f32 v[46:47], v[64:65], v[46:47]
	v_mul_f32_e32 v48, v64, v48
	v_mul_f32_e32 v64, v46, v124
	v_mul_f32_e32 v49, v195, v48
	v_mul_f32_e32 v48, v196, v48
	v_mul_f32_e32 v124, v187, v64
	v_mul_f32_e32 v64, v188, v64
	v_mul_f32_e32 v122, v193, v48
	v_mul_f32_e32 v48, v194, v48
	v_mul_f32_e32 v125, v185, v64
	v_mul_f32_e32 v64, v186, v64
	v_mul_f32_e32 v123, v191, v48
	v_mul_f32_e32 v48, v192, v48
	v_mul_f32_e32 v126, v183, v64
	v_mul_f32_e32 v64, v184, v64
	v_mul_f32_e32 v48, v189, v48
	v_mul_f32_e32 v127, v181, v64
	v_pk_mul_f32 v[64:65], v[46:47], v[46:47] op_sel:[0,1] op_sel_hi:[1,0]
	v_cvt_pk_bf16_f32 v46, v127, v126
	v_cvt_pk_bf16_f32 v47, v125, v124
	v_cvt_pk_bf16_f32 v48, v48, v123
	v_cvt_pk_bf16_f32 v49, v122, v49
	s_nop 1
	v_mfma_f32_32x32x16_bf16 v[18:33], v[118:121], v[46:49], v[18:33]
	v_mfma_f32_32x32x16_bf16 v[2:17], v[114:117], v[46:49], v[2:17]
	v_mul_f32_e32 v46, v62, v205
	v_mul_f32_e32 v47, v207, v209
	v_mul_f32_e32 v46, v46, v47
	v_mov_b32_e32 v47, v46
	s_nop 1
	v_permlane32_swap_b32_e32 v46, v47
	v_cndmask_b32_e64 v48, 1.0, v47, s[44:45]
	v_mul_f32_e32 v48, v64, v48
	v_mul_f32_e32 v49, v220, v48
	v_mul_f32_e32 v48, v209, v48
	v_mul_f32_e32 v62, v208, v48
	v_mul_f32_e32 v48, v207, v48
	v_mul_f32_e32 v63, v63, v48
	v_mul_f32_e32 v48, v205, v48
	v_mul_f32_e32 v45, v45, v48
	v_mul_f32_e32 v46, v46, v47
	v_mul_f32_e32 v47, v58, v59
	v_mul_f32_e32 v48, v60, v61
	v_mul_f32_e32 v65, v47, v48
	v_mov_b32_e32 v47, v65
	s_nop 1
	v_permlane32_swap_b32_e32 v65, v47
	v_cndmask_b32_e64 v48, 1.0, v47, s[44:45]
	v_pk_mul_f32 v[46:47], v[64:65], v[46:47]
	s_nop 0
	v_mul_f32_e32 v48, v46, v48
	v_mul_f32_e32 v44, v44, v48
	v_mul_f32_e32 v48, v61, v48
	v_mul_f32_e32 v43, v43, v48
	v_mul_f32_e32 v48, v60, v48
	v_mul_f32_e32 v42, v42, v48
	v_mul_f32_e32 v48, v59, v48
	v_mul_f32_e32 v41, v41, v48
	v_cvt_pk_bf16_f32 v42, v41, v42
	v_cvt_pk_bf16_f32 v43, v43, v44
	v_cvt_pk_bf16_f32 v44, v45, v63
	v_cvt_pk_bf16_f32 v45, v62, v49
	v_mul_f32_e32 v41, v54, v55
	v_pk_mul_f32 v[46:47], v[46:47], v[46:47] op_sel:[0,1] op_sel_hi:[1,0]
	v_mfma_f32_32x32x16_bf16 v[18:33], v[110:113], v[42:45], v[18:33]
	v_mfma_f32_32x32x16_bf16 v[2:17], v[106:109], v[42:45], v[2:17]
	v_mul_f32_e32 v42, v56, v57
	v_mul_f32_e32 v41, v41, v42
	v_mov_b32_e32 v42, v41
	s_nop 1
	v_permlane32_swap_b32_e32 v41, v42
	v_cndmask_b32_e64 v43, 1.0, v42, s[44:45]
	v_mul_f32_e32 v43, v46, v43
	v_mul_f32_e32 v40, v40, v43
	v_mul_f32_e32 v43, v57, v43
	v_mul_f32_e32 v44, v39, v43
	v_mul_f32_e32 v39, v56, v43
	v_mul_f32_e32 v43, v38, v39
	v_mul_f32_e32 v38, v55, v39
	v_mul_f32_e32 v37, v37, v38
	v_mul_f32_e32 v38, v41, v42
	v_mul_f32_e32 v39, v180, v51
	v_mul_f32_e32 v41, v52, v53
	v_mul_f32_e32 v47, v39, v41
	v_mov_b32_e32 v39, v47
	s_nop 1
	v_permlane32_swap_b32_e32 v47, v39
	v_cndmask_b32_e64 v41, 1.0, v39, s[44:45]
	v_pk_mul_f32 v[38:39], v[46:47], v[38:39]
	s_nop 0
	v_mul_f32_e32 v41, v38, v41
	v_mul_f32_e32 v36, v36, v41
	v_mul_f32_e32 v41, v53, v41
	v_mul_f32_e32 v35, v35, v41
	v_mul_f32_e32 v41, v52, v41
	v_mul_f32_e32 v34, v34, v41
	v_mul_f32_e32 v41, v51, v41
	v_mul_f32_e32 v41, v50, v41
	v_cvt_pk_bf16_f32 v34, v41, v34
	v_cvt_pk_bf16_f32 v35, v35, v36
	v_cvt_pk_bf16_f32 v36, v37, v43
	v_cvt_pk_bf16_f32 v37, v44, v40
	v_mul_f32_e32 v138, v38, v39
	v_cmp_gt_f32_e32 vcc, s94, v138
	v_mfma_f32_32x32x16_bf16 v[18:33], v[102:105], v[34:37], v[18:33]
	s_cmp_eq_u64 vcc, exec
	s_cselect_b64 s[48:49], -1, 0
	v_mfma_f32_32x32x16_bf16 v[2:17], v[98:101], v[34:37], v[2:17]
	s_andn2_b64 vcc, exec, s[38:39]
	s_cbranch_vccnz .LBB0_119
